# FFN-down: weight-prep workgroups start ~8 us after the tile owners (hold-back of the non-critical memory traffic past the K-loop ramp-up)
# speedup vs baseline: 1.0030x; 1.0030x over previous
.LBB0_1054:
	v_readlane_b32 s0, v254, 23
	v_readlane_b32 s1, v254, 24
	s_or_b64 s[0:1], s[0:1], s[6:7]
	v_readlane_b32 s84, v252, 46
	s_and_b64 vcc, exec, s[0:1]
	v_readlane_b32 s85, v252, 47
	s_cbranch_vccnz .LBB0_1121
	v_readlane_b32 s0, v255, 8
	v_readlane_b32 s1, v255, 9
	s_and_b64 s[0:1], s[0:1], exec
	s_movk_i32 s0, 0x200
	s_cselect_b32 s18, 0x100, s0
	s_or_b32 s19, s18, 0x420
	s_lshr_b32 s52, s19, 1
	v_readlane_b32 s0, v254, 27
	v_mov_b32_e32 v0, v192
	s_cmp_ge_u32 s0, s52
	s_cbranch_scc1 .LBB0_1121
	s_sleep 127
	s_sleep 127
	v_readlane_b32 s0, v254, 34
	v_ashrrev_i32_e32 v11, 8, v0
	s_mov_b32 s0, 0xa000
	v_bfe_u32 v55, v0, 4, 4
	v_mad_i32_i24 v3, v11, s0, 0
	s_add_i32 s0, s72, 1
	v_mul_u32_u24_e32 v4, 0x41, v55
	v_lshlrev_b32_e32 v7, 4, v0
	s_lshr_b32 s14, s0, 1
	s_mul_hi_u32 s7, s0, 0x580000
	s_mul_i32 s6, s0, 0x580000
	s_mul_hi_u32 s22, s0, 0xb00000
	s_mul_i32 s23, s0, 0xb00000
	v_lshlrev_b32_e32 v5, 2, v4
	v_and_b32_e32 v4, 0xf0, v7
	v_bfe_u32 v58, v0, 2, 6
	v_and_b32_e32 v7, 48, v7
	s_movk_i32 s0, 0x41
	v_and_b32_e32 v13, 0xff, v0
	s_add_i32 s53, s18, 0x160
	s_add_i32 s54, s18, 0x2c0
	v_add3_u32 v56, v3, v5, v4
	v_add3_u32 v57, v3, v4, v5
	v_mad_u32_u24 v5, v7, s0, v58
	s_lshl_b64 s[0:1], s[14:15], 22
	s_lshl_b64 s[4:5], s[14:15], 23
	v_bfe_u32 v10, v0, 6, 2
	v_and_b32_e32 v12, 63, v0
	v_and_b32_e32 v0, 0xc0, v0
	v_readlane_b32 s20, v253, 60
	s_mov_b32 s56, s87
	v_lshl_add_u32 v59, v5, 2, v3
	v_mul_u32_u24_e32 v5, 0x180000, v10
	v_lshlrev_b32_e32 v9, 2, v12
	v_lshlrev_b32_e32 v0, 2, v0
	v_readlane_b32 s72, v252, 12
	v_readlane_b32 s21, v253, 61
	s_add_u32 s6, s20, s6
	v_add3_u32 v64, v3, v0, v9
	v_lshlrev_b32_e32 v0, 2, v5
	v_readlane_b32 s76, v252, 16
	v_readlane_b32 s77, v252, 17
	s_addc_u32 s7, s21, s7
	s_add_u32 s20, s24, s23
	v_lshl_add_u64 v[14:15], s[76:77], 0, v[0:1]
	v_lshlrev_b32_e32 v0, 1, v7
	s_addc_u32 s21, s25, s22
	v_lshl_add_u64 v[18:19], s[6:7], 0, v[0:1]
	v_readlane_b32 s6, v253, 62
	v_readlane_b32 s7, v253, 63
	s_add_u32 s6, s6, s23
	v_readlane_b32 s64, v252, 0
	v_mov_b32_e32 v5, v1
	s_addc_u32 s7, s7, s22
	v_readlane_b32 s70, v252, 6
	v_lshl_add_u64 v[16:17], s[20:21], 0, v[4:5]
	v_readlane_b32 s71, v252, 7
	s_add_u32 s20, s70, s23
	v_readlane_b32 s68, v252, 4
	s_addc_u32 s21, s71, s22
	v_readlane_b32 s69, v252, 5
	v_lshl_add_u64 v[22:23], s[6:7], 0, v[0:1]
	s_add_u32 s6, s68, s23
	s_addc_u32 s7, s69, s22
	v_lshl_add_u64 v[20:21], s[20:21], 0, v[4:5]
	v_lshl_add_u64 v[24:25], s[6:7], 0, v[4:5]
	s_lshl_b64 s[6:7], s[14:15], 21
	v_readlane_b32 s20, v253, 43
	v_readlane_b32 s21, v253, 44
	s_add_u32 s6, s20, s6
	v_readlane_b32 s82, v252, 22
	s_addc_u32 s7, s21, s7
	v_readlane_b32 s83, v252, 23
	s_add_u32 s20, s82, s0
	s_mul_i32 s41, s14, 0x600000
	s_addc_u32 s21, s83, s1
	s_mul_hi_u32 s40, s14, 0x600000
	v_lshl_add_u64 v[28:29], s[6:7], 0, v[0:1]
	s_add_u32 s6, s28, s41
	s_mul_i32 s43, s14, 0xc00000
	v_readlane_b32 s80, v252, 20
	s_addc_u32 s7, s29, s40
	s_mul_hi_u32 s42, s14, 0xc00000
	v_readlane_b32 s81, v252, 21
	v_lshl_add_u64 v[26:27], s[20:21], 0, v[4:5]
	s_add_u32 s20, s80, s43
	s_addc_u32 s21, s81, s42
	v_lshl_add_u64 v[32:33], s[6:7], 0, v[0:1]
	v_readlane_b32 s6, v253, 17
	s_add_u32 s0, s6, s0
	v_readlane_b32 s6, v253, 18
	v_readlane_b32 s66, v252, 2
	s_addc_u32 s1, s6, s1
	v_mul_i32_i24_e32 v6, 0xa000, v11
	v_lshlrev_b32_e32 v2, 2, v13
	v_mul_u32_u24_e32 v8, 0x300, v10
	v_readlane_b32 s84, v252, 24
	v_readlane_b32 s85, v252, 25
	v_readlane_b32 s67, v252, 3
	s_add_u32 s4, s66, s4
	v_add_u32_e32 v61, v3, v2
	v_lshl_add_u32 v62, v10, 10, v3
	v_add3_u32 v63, v3, v8, v9
	s_movk_i32 s2, 0xc0
	v_readlane_b32 s84, v252, 46
	s_addc_u32 s5, s67, s5
	v_lshl_add_u64 v[36:37], s[0:1], 0, v[0:1]
	v_mov_b32_e32 v3, v1
	v_or_b32_e32 v0, v6, v2
	s_add_i32 s0, 0, 0x1000
	v_bfe_u32 v60, v13, 2, 4
	v_cmp_gt_u32_e64 s[2:3], s2, v13
	v_readlane_b32 s85, v252, 47
	s_mov_b32 s80, 0x24000
	s_mov_b32 s57, 0x12000
	v_lshl_add_u64 v[30:31], s[20:21], 0, v[4:5]
	v_lshl_add_u64 v[34:35], s[4:5], 0, v[4:5]
	v_lshl_add_u64 v[38:39], s[50:51], 0, v[2:3]
	v_or_b32_e32 v65, 0x300, v13
	v_add_u32_e32 v66, s0, v0
	v_readlane_b32 s14, v254, 27
	v_readlane_b32 s73, v252, 13
	v_readlane_b32 s74, v252, 14
	v_readlane_b32 s75, v252, 15
	v_readlane_b32 s78, v252, 18
	v_readlane_b32 s79, v252, 19
	v_readlane_b32 s86, v252, 26
	v_readlane_b32 s87, v252, 27
	v_readlane_b32 s65, v252, 1
	s_branch .LBB0_1059
